# cross-attention KV loop: staging addresses hoisted (invariant LDS address and lane offsets, SGPR tile bases), on top of v33
# speedup vs baseline: 1.0173x; 1.0000x over previous
; DI int tid_opaque() { int t = threadIdx.x; asm volatile("" : "+v"(t)); return t; }
; template <int DK, int DV, int MODE>
; DI void att_gload(const AttArgs& a, int tile, u32x4 (&kr)[(64 * (DK / 8) + NT - 1) / NT], u32x4 (&vr)[(64 * (DV / 8) + NT - 1) / NT]) {
;   constexpr int CK = DK / 8, CV = DV / 8;
;   constexpr int NKL = (64 * CK + NT - 1) / NT, NVL = (64 * CV + NT - 1) / NT;
;   const int t = tid_opaque();
;   const int kbase = tile * 64;
; #pragma unroll
;   for (int i = 0; i < NKL; ++i) {
;     const int id = min(t + NT * i, 64 * CK - 1);
;     const int row = id / CK, c = id % CK;
;     if constexpr (MODE == 3) {
;       const bf16_t* src = (c < 8) ? (a.k + (size_t)(kbase + row) * a.ldk + c * 8) : (a.k2 + (size_t)(kbase + row) * a.ldk2 + (c - 8) * 8);
;       kr[i] = *(const u32x4*)src;
;     } else {
;       kr[i] = *(const u32x4*)(a.k + (size_t)(kbase + row) * a.ldk + c * 8);
;     }
;   }
; #pragma unroll
;   for (int i = 0; i < NVL; ++i) {
;     const int id = t + NT * i;
;     const int row = id / CV, c = id % CV;
;     vr[i] = *(const u32x4*)(a.v + (size_t)(kbase + row) * a.ldv + c * 8);
;   }
; }
; template <int DK, int DV, int MODE, int QB, bool PACK = false>
; DI void attn_item(const AttArgs& a, int q0, int t_lo, int t_hi) {
;     ...
;   bf16x8 qf[QB][NKS];
; #pragma unroll
;   for (int qb = 0; qb < QB; ++qb) {
;     const bf16_t* qp = a.q + hg * DK + (size_t)(wq0 + qb * 32 + r) * a.ldq + h * 8;
; #pragma unroll
;     for (int s = 0; s < NKS; ++s) qf[qb][s] = *(const bf16x8*)(qp + s * 16);
;   }
;   f32x16 o[QB][NDB];
;   float m[QB], lsum[QB];
; #pragma unroll
;   for (int qb = 0; qb < QB; ++qb) {
;     m[qb] = -1e30f; lsum[qb] = 0.f;
; #pragma unroll
;     for (int d = 0; d < NDB; ++d)
; #pragma unroll
;       for (int i = 0; i < 16; ++i) o[qb][d][i] = 0.f;
;   }
;   u32x4 kr[NKL], vr[NVL];
;   att_gload<DK, DV, MODE>(a, t_lo, kr, vr);
;   att_swrite<DK, DV>(0, kr, vr);
;   if (t_lo + 1 < t_hi) att_gload<DK, DV, MODE>(a, t_lo + 1, kr, vr);
;   __syncthreads();
;   const float scale = a.scale;
;   const float cexp = (MODE == 2) ? LOG2E : a.scale * LOG2E;
;   const int vq = (l & 15) >> 2, vp = l & 3, vblk = (l >> 4) & 1;
.LBB0_1083:
	s_or_b64 exec, exec, s[8:9]
	s_waitcnt vmcnt(2)
	v_add_u32_e32 v4, v22, v23
	v_lshrrev_b32_e32 v5, 4, v4
	v_and_b32_e32 v4, 0xffffff0, v4
	s_movk_i32 s8, 0x110
	v_sub_u32_e32 v4, v22, v4
	v_mul_lo_u32 v5, v5, s8
	v_lshl_add_u32 v4, v4, 4, v5
	s_waitcnt vmcnt(1)
	ds_write_b128 v4, v[12:15] offset:17408
	v_add_u32_e32 v4, v16, v17
	s_waitcnt vmcnt(0)
	ds_write_b128 v4, v[8:11] offset:17408
	v_mov_b32_e32 v10, v224
	s_mov_b32 s8, 0x20000
	v_min_i32_e32 v5, 0x3ff, v10
	v_ashrrev_i32_e32 v4, 31, v5
	v_lshrrev_b32_e32 v4, 28, v4
	v_add_u32_e32 v6, v5, v4
	v_ashrrev_i32_e32 v4, 4, v6
	v_and_b32_e32 v6, 0x1ffffff0, v6
	v_sub_u32_e32 v6, v5, v6
	v_ashrrev_i32_e32 v5, 31, v4
	v_lshlrev_b64 v[4:5], 11, v[4:5]
	v_lshlrev_b32_e32 v6, 3, v6
	v_lshl_add_u64 v[4:5], s[2:3], 0, v[4:5]
	v_ashrrev_i32_e32 v7, 31, v6
	v_add_u32_e32 v11, 0x200, v10
	v_lshl_add_u64 v[4:5], v[6:7], 1, v[4:5]
	v_min_i32_e32 v7, 0x3ff, v11
	v_ashrrev_i32_e32 v6, 31, v7
	v_lshrrev_b32_e32 v6, 28, v6
	v_add_u32_e32 v8, v7, v6
	v_ashrrev_i32_e32 v6, 4, v8
	v_and_b32_e32 v8, 0x1ffffff0, v8
	v_sub_u32_e32 v8, v7, v8
	v_ashrrev_i32_e32 v7, 31, v6
	v_lshlrev_b64 v[6:7], 11, v[6:7]
	v_lshlrev_b32_e32 v8, 3, v8
	v_add_co_u32_e32 v4, vcc, s8, v4
	v_lshl_add_u64 v[6:7], s[2:3], 0, v[6:7]
	v_ashrrev_i32_e32 v9, 31, v8
	v_addc_co_u32_e32 v5, vcc, 0, v5, vcc
	v_lshl_add_u64 v[6:7], v[8:9], 1, v[6:7]
	v_add_co_u32_e32 v6, vcc, s8, v6
	v_lshlrev_b64 v[160:161], 9, v[0:1]
	s_nop 0
	v_addc_co_u32_e32 v7, vcc, 0, v7, vcc
	global_load_dwordx4 v[144:147], v[4:5], off
	global_load_dwordx4 v[148:151], v[6:7], off
	v_ashrrev_i32_e32 v4, 31, v10
	v_lshrrev_b32_e32 v4, 28, v4
	v_add_u32_e32 v5, v10, v4
	v_ashrrev_i32_e32 v4, 4, v5
	v_and_b32_e32 v5, 0x1ffffff0, v5
	v_sub_u32_e32 v6, v10, v5
	v_ashrrev_i32_e32 v5, 31, v4
	v_lshlrev_b64 v[4:5], 11, v[4:5]
	v_lshlrev_b32_e32 v6, 3, v6
	v_lshl_add_u64 v[4:5], s[6:7], 0, v[4:5]
	v_ashrrev_i32_e32 v7, 31, v6
	v_lshl_add_u64 v[4:5], v[6:7], 1, v[4:5]
	v_ashrrev_i32_e32 v6, 31, v11
	v_lshrrev_b32_e32 v6, 28, v6
	v_add_u32_e32 v7, v11, v6
	v_ashrrev_i32_e32 v6, 4, v7
	v_and_b32_e32 v7, 0x1ffffff0, v7
	v_sub_u32_e32 v8, v11, v7
	v_ashrrev_i32_e32 v7, 31, v6
	v_lshlrev_b64 v[6:7], 11, v[6:7]
	v_lshlrev_b32_e32 v8, 3, v8
	v_add_co_u32_e32 v4, vcc, s8, v4
	v_lshl_add_u64 v[6:7], s[6:7], 0, v[6:7]
	v_ashrrev_i32_e32 v9, 31, v8
	v_addc_co_u32_e32 v5, vcc, 0, v5, vcc
	v_lshl_add_u64 v[6:7], v[8:9], 1, v[6:7]
	v_add_co_u32_e32 v6, vcc, s8, v6
	v_bfe_u32 v0, v3, 2, 2
	s_nop 0
	v_addc_co_u32_e32 v7, vcc, 0, v7, vcc
	global_load_dwordx4 v[152:155], v[4:5], off
	global_load_dwordx4 v[156:159], v[6:7], off
	v_and_b32_e32 v1, 16, v3
	v_lshlrev_b32_e32 v3, 2, v3
	v_lshl_or_b32 v0, v21, 2, v0
	v_and_or_b32 v1, v3, 12, v1
	v_mov_b32_e32 v14, v2
	v_mov_b32_e32 v15, v2
	v_lshlrev_b32_e32 v163, 3, v21
	v_lshlrev_b32_e32 v165, 1, v1
	v_mul_u32_u24_e32 v167, 0x110, v20
	v_mul_u32_u24_e32 v166, 0x110, v0
	v_mov_b32_e32 v0, v2
	v_mov_b32_e32 v1, v2
	v_mov_b32_e32 v3, v2
	v_mov_b32_e32 v4, v2
	v_mov_b32_e32 v5, v2
	v_mov_b32_e32 v6, v2
	v_mov_b32_e32 v7, v2
	v_mov_b32_e32 v8, v2
	v_mov_b32_e32 v9, v2
	v_mov_b32_e32 v10, v2
	v_mov_b32_e32 v11, v2
	v_mov_b32_e32 v12, v2
	v_mov_b32_e32 v13, v2
	v_mov_b64_e32 v[30:31], v[14:15]
	v_mov_b64_e32 v[46:47], v[14:15]
	v_mov_b64_e32 v[62:63], v[14:15]
	v_mov_b64_e32 v[78:79], v[14:15]
	s_lshl_b64 s[4:5], s[4:5], 20
	s_mov_b32 s20, 0
	v_mov_b32_e32 v168, 0xf149f2ca
	v_mov_b32_e32 v164, 0
	s_mov_b64 s[8:9], 0x80
	v_mov_b64_e32 v[28:29], v[12:13]
	v_mov_b64_e32 v[26:27], v[10:11]
	v_mov_b64_e32 v[24:25], v[8:9]
	v_mov_b64_e32 v[22:23], v[6:7]
	v_mov_b64_e32 v[20:21], v[4:5]
	v_mov_b64_e32 v[18:19], v[2:3]
	v_mov_b64_e32 v[16:17], v[0:1]
	v_mov_b64_e32 v[44:45], v[12:13]
	v_mov_b64_e32 v[42:43], v[10:11]
	v_mov_b64_e32 v[40:41], v[8:9]
	v_mov_b64_e32 v[38:39], v[6:7]
	v_mov_b64_e32 v[36:37], v[4:5]
	v_mov_b64_e32 v[34:35], v[2:3]
	v_mov_b64_e32 v[32:33], v[0:1]
	v_mov_b64_e32 v[60:61], v[12:13]
	v_mov_b64_e32 v[58:59], v[10:11]
	v_mov_b64_e32 v[56:57], v[8:9]
	v_mov_b64_e32 v[54:55], v[6:7]
	v_mov_b64_e32 v[52:53], v[4:5]
	v_mov_b64_e32 v[50:51], v[2:3]
	v_mov_b64_e32 v[48:49], v[0:1]
	v_mov_b64_e32 v[76:77], v[12:13]
	v_mov_b64_e32 v[74:75], v[10:11]
	v_mov_b64_e32 v[72:73], v[8:9]
	v_mov_b64_e32 v[70:71], v[6:7]
	v_mov_b64_e32 v[68:69], v[4:5]
	v_mov_b64_e32 v[66:67], v[2:3]
	v_mov_b64_e32 v[64:65], v[0:1]
	v_lshrrev_b32_e32 v220, 4, v224
	v_and_b32_e32 v221, 15, v224
	v_lshlrev_b32_e32 v222, 11, v220
	v_mul_u32_u24_e32 v220, 0x110, v220
	v_lshl_add_u32 v220, v221, 4, v220
	v_lshl_or_b32 v221, v221, 4, v222
	v_add_u32_e32 v222, 0x10000, v221
	s_waitcnt lgkmcnt(0)
	s_barrier
	s_branch .LBB0_1085

; DI int tid_opaque() { int t = threadIdx.x; asm volatile("" : "+v"(t)); return t; }
; template <int DK, int DV, int MODE>
; DI void att_gload(const AttArgs& a, int tile, u32x4 (&kr)[(64 * (DK / 8) + NT - 1) / NT], u32x4 (&vr)[(64 * (DV / 8) + NT - 1) / NT]) {
;   constexpr int CK = DK / 8, CV = DV / 8;
;   constexpr int NKL = (64 * CK + NT - 1) / NT, NVL = (64 * CV + NT - 1) / NT;
;   const int t = tid_opaque();
;   const int kbase = tile * 64;
; #pragma unroll
;   for (int i = 0; i < NKL; ++i) {
;     const int id = min(t + NT * i, 64 * CK - 1);
;     const int row = id / CK, c = id % CK;
;     if constexpr (MODE == 3) {
;       const bf16_t* src = (c < 8) ? (a.k + (size_t)(kbase + row) * a.ldk + c * 8) : (a.k2 + (size_t)(kbase + row) * a.ldk2 + (c - 8) * 8);
;       kr[i] = *(const u32x4*)src;
;     } else {
;       kr[i] = *(const u32x4*)(a.k + (size_t)(kbase + row) * a.ldk + c * 8);
;     }
;   }
; #pragma unroll
;   for (int i = 0; i < NVL; ++i) {
;     const int id = t + NT * i;
;     const int row = id / CV, c = id % CV;
;     vr[i] = *(const u32x4*)(a.v + (size_t)(kbase + row) * a.ldv + c * 8);
;   }
; }
; template <int DK, int DV>
; DI void att_swrite(int buf, const u32x4 (&kr)[(64 * (DK / 8) + NT - 1) / NT], const u32x4 (&vr)[(64 * (DV / 8) + NT - 1) / NT]) {
;   constexpr int CK = DK / 8, CV = DV / 8;
;   constexpr int KST = DK * 2 + 16, VST = DV * 2 + 16;
;   constexpr int KBYTES = 64 * KST, VBYTES = 64 * VST, BUFB = KBYTES + VBYTES;
;   constexpr int NKL = (64 * CK + NT - 1) / NT, NVL = (64 * CV + NT - 1) / NT;
;   const int t = tid_opaque();
; #pragma unroll
;   for (int i = 0; i < NKL; ++i) {
;     const int id = t + NT * i;
;     const int row = id / CK, c = id % CK;
;     if (id < 64 * CK) *(u32x4*)(smem + buf * BUFB + row * KST + c * 16) = kr[i];
;   }
; #pragma unroll
;   for (int i = 0; i < NVL; ++i) {
;     const int id = t + NT * i;
;     const int row = id / CV, c = id % CV;
;     *(u32x4*)(smem + buf * BUFB + KBYTES + row * VST + c * 16) = vr[i];
;   }
; }
.LBB0_1085:
	s_and_b32 s21, s20, 1
	s_xor_b32 s24, s21, 1
	s_mul_i32 s24, s24, 0x8800
	v_add_u32_e32 v0, s24, v220
	s_waitcnt vmcnt(3)
	ds_write_b128 v0, v[144:147]
	s_waitcnt vmcnt(2)
	ds_write_b128 v0, v[148:151] offset:8704
	s_waitcnt vmcnt(1)
	ds_write_b128 v0, v[152:155] offset:17408
	s_cmp_gt_u32 s20, 1
	s_waitcnt vmcnt(0)
	ds_write_b128 v0, v[156:159] offset:26112
	s_cbranch_scc1 .LBB0_1093
	s_lshl_b64 s[12:13], s[8:9], 11
	s_add_u32 s24, s12, s2
	s_addc_u32 s25, s13, s3
	global_load_dwordx4 v[144:147], v221, s[24:25]
	global_load_dwordx4 v[148:151], v222, s[24:25]
	s_add_u32 s12, s12, s6
	s_addc_u32 s13, s13, s7
	global_load_dwordx4 v[152:155], v221, s[12:13]
	global_load_dwordx4 v[156:159], v222, s[12:13]
